# S7 context-row tiles: batched fragment loads, cross-tile prefetch, batched reduction reads
# speedup vs baseline: 1.0210x; 1.0024x over previous
; #define LAS __attribute__((address_space(3)))
; template <int MODE>
; DEV void cgemm_tile(const Fr& F, const bf16_t* A, const bf16_t* Bt, int K, int rb, int cb, bf16_t* O, int ldc) {
;     LAS float* part = (LAS float*)F.lds;
;     const int w = F.wave, fr = F.lane & 15, fq = F.lane >> 4;
;     const int arow0 = (rb >> 2) * RPB + (rb & 3) * 64;
;     int brow[4];
; #pragma unroll
;     for (int ni = 0; ni < 4; ++ni) {
;         if (MODE == 0) brow[ni] = cb * 64 + ni * 16;
;         else { const int j = cb * 32 + (ni & 1) * 16; brow[ni] = (j >> 7) * 256 + (ni >> 1) * 128 + (j & 127); }
;     }
;     const int kslice = K >> 3, steps = kslice >> 5;
;     const bf16_t* ap = A + (size_t)(arow0 + fr) * K + w * kslice + 8 * fq;
;     const bf16_t* bp = Bt + (size_t)fr * K + w * kslice + 8 * fq;
;     f32x4 acc[4][4];
; #pragma unroll
;     for (int mi = 0; mi < 4; ++mi)
; #pragma unroll
;         for (int ni = 0; ni < 4; ++ni) acc[mi][ni] = (f32x4){0.f, 0.f, 0.f, 0.f};
;     int s = 0;
;     for (; s + 4 <= steps; s += 4) cg_chunk<4>(acc, ap + s * 32, bp + s * 32, brow, K);
.LBB0_1257:
	v_mov_b32_e32 v1, v188
	s_and_b64 vcc, exec, s[38:39]
	v_readfirstlane_b32 s0, v1
	s_cbranch_vccnz .LBB0_1279
	v_and_b32_e32 v56, 63, v1
	s_ashr_i32 s15, s0, 6
	s_and_b64 vcc, exec, s[74:75]
	s_mov_b64 s[0:1], -1
	s_cbranch_vccnz .LBB0_1265
	v_readlane_b32 s0, v240, 23
	v_readlane_b32 s1, v240, 24
	s_andn2_b64 vcc, exec, s[0:1]
	s_cbranch_vccnz .LBB0_1264
	s_waitcnt vmcnt(0)
	v_and_b32_e32 v8, 15, v1
	v_readlane_b32 s6, v242, 31
	s_lshl_b32 s0, s15, 7
	v_mov_b32_e32 v3, v0
	v_or_b32_e32 v2, s6, v8
	v_lshlrev_b32_e32 v2, 11, v2
	s_ashr_i32 s1, s0, 31
	v_lshlrev_b32_e32 v4, 11, v8
	v_mov_b32_e32 v5, v0
	s_lshl_b64 s[0:1], s[0:1], 1
	v_lshl_add_u64 v[2:3], s[12:13], 0, v[2:3]
	v_lshl_add_u64 v[4:5], s[2:3], 0, v[4:5]
	v_lshl_add_u64 v[2:3], v[2:3], 0, s[0:1]
	v_and_b32_e32 v6, 48, v56
	v_mov_b32_e32 v7, v0
	v_lshl_add_u64 v[4:5], v[4:5], 0, s[0:1]
	v_lshl_add_u64 v[18:19], v[2:3], 0, v[6:7]
	s_mov_b64 s[0:1], 0x8000
	v_lshl_add_u64 v[22:23], v[18:19], 0, s[0:1]
	s_mov_b64 s[0:1], 0x10000
	v_lshl_add_u64 v[24:25], v[18:19], 0, s[0:1]
	s_mov_b64 s[0:1], 0x18000
	v_lshl_add_u64 v[26:27], v[18:19], 0, s[0:1]
	s_mov_b64 s[0:1], 0x8040
	v_lshl_add_u64 v[28:29], v[18:19], 0, s[0:1]
	s_mov_b64 s[0:1], 0x10040
	v_lshl_add_u64 v[30:31], v[18:19], 0, s[0:1]
	s_mov_b64 s[0:1], 0x18040
	v_lshl_add_u64 v[32:33], v[18:19], 0, s[0:1]
	s_mov_b64 s[0:1], 0x8080
	v_lshl_add_u64 v[34:35], v[18:19], 0, s[0:1]
	s_mov_b64 s[0:1], 0x10080
	v_lshl_add_u64 v[36:37], v[18:19], 0, s[0:1]
	s_mov_b64 s[0:1], 0x18080
	v_lshl_add_u64 v[38:39], v[18:19], 0, s[0:1]
	s_mov_b64 s[0:1], 0x80c0
	v_lshl_add_u64 v[40:41], v[18:19], 0, s[0:1]
	s_mov_b64 s[0:1], 0x100c0
	v_lshl_add_u64 v[42:43], v[18:19], 0, s[0:1]
	s_mov_b64 s[0:1], 0x180c0
	v_lshl_add_u64 v[44:45], v[18:19], 0, s[0:1]
	s_lshl_b32 s0, s15, 14
	v_lshl_add_u64 v[20:21], v[4:5], 0, v[6:7]
	v_lshrrev_b32_e32 v2, 2, v56
	v_lshlrev_b32_e32 v4, 2, v8
	s_add_i32 s0, s0, 0
	v_and_b32_e32 v3, 12, v2
	v_lshl_add_u32 v5, v8, 8, s0
	v_bitop3_b32 v2, v2, v4, 12 bitop3:0x6c
	v_lshl_add_u32 v57, v2, 2, v5
	v_bitop3_b32 v2, v3, v4, 16 bitop3:0x36
	v_lshl_add_u32 v58, v2, 2, v5
	v_bitop3_b32 v2, v3, v4, 32 bitop3:0x36
	v_lshl_add_u32 v59, v2, 2, v5
	v_bitop3_b32 v2, v3, v4, 48 bitop3:0x36
	v_lshl_add_u32 v60, v2, 2, v5
	v_lshlrev_b32_e32 v2, 3, v1
	v_and_b32_e32 v4, 56, v2
	v_ashrrev_i32_e32 v2, 3, v1
	v_lshlrev_b32_e32 v3, 2, v2
	v_and_b32_e32 v5, 60, v3
	v_lshl_add_u32 v6, v2, 8, 0
	v_bitop3_b32 v3, v3, v4, 60 bitop3:0x6c
	v_bitop3_b32 v7, v4, v5, 4 bitop3:0x36
	v_bitop3_b32 v8, v4, v5, 32 bitop3:0x36
	v_bitop3_b32 v5, v4, v5, 36 bitop3:0x36
	v_lshlrev_b32_e32 v3, 2, v3
	v_lshlrev_b32_e32 v7, 2, v7
	v_lshlrev_b32_e32 v8, 2, v8
	v_lshlrev_b32_e32 v5, 2, v5
	v_add_u32_e32 v9, 0x10000, v6
	v_add_u32_e32 v65, v9, v3
	v_add_u32_e32 v66, v9, v7
	v_add_u32_e32 v67, v9, v8
	v_add_u32_e32 v68, v9, v5
	v_add_u32_e32 v9, 0x14000, v6
	v_add_u32_e32 v61, v6, v3
	v_add_u32_e32 v62, v6, v7
	v_add_u32_e32 v63, v6, v8
	v_add_u32_e32 v64, v6, v5
	v_add_u32_e32 v69, v9, v3
	v_add_u32_e32 v70, v9, v7
	v_add_u32_e32 v71, v9, v8
	v_add_u32_e32 v72, v9, v5
	v_add_u32_e32 v9, 0x18000, v6
	v_add_u32_e32 v6, 0x1c000, v6
	v_add_u32_e32 v73, v9, v3
	v_add_u32_e32 v76, v9, v5
	v_add_u32_e32 v77, v6, v3
	v_add_u32_e32 v80, v6, v5
	v_add_u32_e32 v5, s6, v2
	v_mov_b64_e32 v[2:3], s[78:79]
	s_movk_i32 s0, 0x1600
	v_cmp_gt_u32_e32 vcc, 32, v4
	v_mad_i64_i32 v[2:3], s[0:1], v5, s0, v[2:3]
	v_lshlrev_b32_e32 v4, 1, v4
	v_mov_b32_e32 v5, v0
	v_add_u32_e32 v74, v9, v7
	v_add_u32_e32 v75, v9, v8
	v_add_u32_e32 v78, v6, v7
	v_add_u32_e32 v79, v6, v8
	v_lshl_add_u64 v[46:47], v[2:3], 0, v[4:5]
	v_readlane_b32 s6, v240, 47
	v_readlane_b32 s0, v240, 49
	v_readlane_b32 s7, v240, 46
	s_and_b32 s1, s6, 0xffffff00
	s_and_b32 s16, s0, 0x60
	s_or_b32 s16, s16, s1
	s_ashr_i32 s17, s16, 31
	s_lshl_b64 s[18:19], s[16:17], 11
	v_lshl_add_u64 v[48:49], v[20:21], 0, s[18:19]
	s_or_b32 s18, s16, 16
	s_or_b32 s20, s16, 0x80
	s_ashr_i32 s19, s18, 31
	s_or_b32 s16, s16, 0x90
	s_ashr_i32 s21, s20, 31
	s_lshl_b64 s[18:19], s[18:19], 11
	s_ashr_i32 s17, s16, 31
	v_lshl_add_u64 v[54:55], v[20:21], 0, s[18:19]
	s_lshl_b64 s[18:19], s[20:21], 11
	s_lshl_b64 s[16:17], s[16:17], 11
	v_lshl_add_u64 v[52:53], v[20:21], 0, s[18:19]
	v_lshl_add_u64 v[50:51], v[20:21], 0, s[16:17]
	global_load_dwordx4 v[158:161], v[48:49], off
	global_load_dwordx4 v[162:165], v[54:55], off
	global_load_dwordx4 v[166:169], v[52:53], off
	global_load_dwordx4 v[170:173], v[50:51], off
	global_load_dwordx4 v[174:177], v[18:19], off
	global_load_dwordx4 v[178:181], v[22:23], off
	global_load_dwordx4 v[182:185], v[24:25], off
	global_load_dwordx4 v[198:201], v[26:27], off
	global_load_dwordx4 v[202:205], v[48:49], off offset:64
	global_load_dwordx4 v[206:209], v[54:55], off offset:64
	global_load_dwordx4 v[210:213], v[52:53], off offset:64
	global_load_dwordx4 v[214:217], v[50:51], off offset:64
	global_load_dwordx4 v[218:221], v[18:19], off offset:64
	global_load_dwordx4 v[222:225], v[22:23], off offset:64
	global_load_dwordx4 v[226:229], v[24:25], off offset:64
	global_load_dwordx4 v[230:233], v[26:27], off offset:64
	s_branch .LBB0_1262

; template <int CH>
; DEV void cg_chunk(f32x4 (&acc)[4][4], const bf16_t* ap, const bf16_t* bp, const int (&brow)[4], int K) {
;     bf16x8 a[CH][4], b[CH][4];
; #pragma unroll
;     for (int c = 0; c < CH; ++c)
; #pragma unroll
;         for (int i = 0; i < 4; ++i) { a[c][i] = *(const bf16x8*)(ap + (size_t)(16 * i) * K + 32 * c); b[c][i] = *(const bf16x8*)(bp + (size_t)brow[i] * K + 32 * c); }
; #pragma unroll
;     for (int c = 0; c < CH; ++c)
; #pragma unroll
;         for (int mi = 0; mi < 4; ++mi)
; #pragma unroll
;             for (int ni = 0; ni < 4; ++ni) acc[mi][ni] = __builtin_amdgcn_mfma_f32_16x16x32_bf16(b[c][ni], a[c][mi], acc[mi][ni], 0, 0, 0);
; }
.LBB0_1262:
	s_and_b32 s1, s6, 0xffffff00
	s_and_b32 s16, s0, 0x60
	s_or_b32 s16, s16, s1
	s_ashr_i32 s17, s16, 31
	s_lshl_b64 s[18:19], s[16:17], 11
	v_lshl_add_u64 v[48:49], v[20:21], 0, s[18:19]
	s_or_b32 s18, s16, 16
	s_or_b32 s20, s16, 0x80
	s_ashr_i32 s19, s18, 31
	s_or_b32 s16, s16, 0x90
	s_ashr_i32 s21, s20, 31
	s_lshl_b64 s[18:19], s[18:19], 11
	s_ashr_i32 s17, s16, 31
	v_lshl_add_u64 v[54:55], v[20:21], 0, s[18:19]
	s_lshl_b64 s[18:19], s[20:21], 11
	s_lshl_b64 s[16:17], s[16:17], 11
	v_lshl_add_u64 v[52:53], v[20:21], 0, s[18:19]
	v_lshl_add_u64 v[50:51], v[20:21], 0, s[16:17]
	s_waitcnt vmcnt(8)
	v_mfma_f32_16x16x32_bf16 v[82:85], v[158:161], v[174:177], 0
	v_mfma_f32_16x16x32_bf16 v[86:89], v[162:165], v[174:177], 0
	v_mfma_f32_16x16x32_bf16 v[90:93], v[166:169], v[174:177], 0
	v_mfma_f32_16x16x32_bf16 v[94:97], v[170:173], v[174:177], 0
	v_mfma_f32_16x16x32_bf16 v[98:101], v[158:161], v[178:181], 0
	v_mfma_f32_16x16x32_bf16 v[102:105], v[162:165], v[178:181], 0
	v_mfma_f32_16x16x32_bf16 v[106:109], v[166:169], v[178:181], 0
	v_mfma_f32_16x16x32_bf16 v[110:113], v[170:173], v[178:181], 0
	v_mfma_f32_16x16x32_bf16 v[114:117], v[158:161], v[182:185], 0
	v_mfma_f32_16x16x32_bf16 v[118:121], v[162:165], v[182:185], 0
	v_mfma_f32_16x16x32_bf16 v[122:125], v[166:169], v[182:185], 0
	v_mfma_f32_16x16x32_bf16 v[126:129], v[170:173], v[182:185], 0
	v_mfma_f32_16x16x32_bf16 v[130:133], v[158:161], v[198:201], 0
	v_mfma_f32_16x16x32_bf16 v[134:137], v[162:165], v[198:201], 0
	v_mfma_f32_16x16x32_bf16 v[150:153], v[166:169], v[198:201], 0
	v_mfma_f32_16x16x32_bf16 v[154:157], v[170:173], v[198:201], 0
	global_load_dwordx4 v[158:161], v[48:49], off offset:128
	global_load_dwordx4 v[162:165], v[54:55], off offset:128
	global_load_dwordx4 v[166:169], v[52:53], off offset:128
	global_load_dwordx4 v[170:173], v[50:51], off offset:128
	global_load_dwordx4 v[174:177], v[18:19], off offset:128
	global_load_dwordx4 v[178:181], v[22:23], off offset:128
	global_load_dwordx4 v[182:185], v[24:25], off offset:128
	global_load_dwordx4 v[198:201], v[26:27], off offset:128
	s_waitcnt vmcnt(8)
	v_mfma_f32_16x16x32_bf16 v[82:85], v[202:205], v[218:221], v[82:85]
	v_mfma_f32_16x16x32_bf16 v[86:89], v[206:209], v[218:221], v[86:89]
	v_mfma_f32_16x16x32_bf16 v[90:93], v[210:213], v[218:221], v[90:93]
	v_mfma_f32_16x16x32_bf16 v[94:97], v[214:217], v[218:221], v[94:97]
	v_mfma_f32_16x16x32_bf16 v[98:101], v[202:205], v[222:225], v[98:101]
	v_mfma_f32_16x16x32_bf16 v[102:105], v[206:209], v[222:225], v[102:105]
	v_mfma_f32_16x16x32_bf16 v[106:109], v[210:213], v[222:225], v[106:109]
	v_mfma_f32_16x16x32_bf16 v[110:113], v[214:217], v[222:225], v[110:113]
	v_mfma_f32_16x16x32_bf16 v[114:117], v[202:205], v[226:229], v[114:117]
	v_mfma_f32_16x16x32_bf16 v[118:121], v[206:209], v[226:229], v[118:121]
	v_mfma_f32_16x16x32_bf16 v[122:125], v[210:213], v[226:229], v[122:125]
	v_mfma_f32_16x16x32_bf16 v[126:129], v[214:217], v[226:229], v[126:129]
	v_mfma_f32_16x16x32_bf16 v[130:133], v[202:205], v[230:233], v[130:133]
	v_mfma_f32_16x16x32_bf16 v[134:137], v[206:209], v[230:233], v[134:137]
	v_mfma_f32_16x16x32_bf16 v[150:153], v[210:213], v[230:233], v[150:153]
	v_mfma_f32_16x16x32_bf16 v[154:157], v[214:217], v[230:233], v[154:157]
	global_load_dwordx4 v[202:205], v[48:49], off offset:192
	global_load_dwordx4 v[206:209], v[54:55], off offset:192
	global_load_dwordx4 v[210:213], v[52:53], off offset:192
	global_load_dwordx4 v[214:217], v[50:51], off offset:192
	global_load_dwordx4 v[218:221], v[18:19], off offset:192
	global_load_dwordx4 v[222:225], v[22:23], off offset:192
	global_load_dwordx4 v[226:229], v[24:25], off offset:192
	global_load_dwordx4 v[230:233], v[26:27], off offset:192
	s_waitcnt vmcnt(8)
	v_mfma_f32_16x16x32_bf16 v[82:85], v[158:161], v[174:177], v[82:85]
	v_mfma_f32_16x16x32_bf16 v[86:89], v[162:165], v[174:177], v[86:89]
	v_mfma_f32_16x16x32_bf16 v[90:93], v[166:169], v[174:177], v[90:93]
	v_mfma_f32_16x16x32_bf16 v[94:97], v[170:173], v[174:177], v[94:97]
	v_mfma_f32_16x16x32_bf16 v[98:101], v[158:161], v[178:181], v[98:101]
	v_mfma_f32_16x16x32_bf16 v[102:105], v[162:165], v[178:181], v[102:105]
	v_mfma_f32_16x16x32_bf16 v[106:109], v[166:169], v[178:181], v[106:109]
	v_mfma_f32_16x16x32_bf16 v[110:113], v[170:173], v[178:181], v[110:113]
	v_mfma_f32_16x16x32_bf16 v[114:117], v[158:161], v[182:185], v[114:117]
	v_mfma_f32_16x16x32_bf16 v[118:121], v[162:165], v[182:185], v[118:121]
	v_mfma_f32_16x16x32_bf16 v[122:125], v[166:169], v[182:185], v[122:125]
	v_mfma_f32_16x16x32_bf16 v[126:129], v[170:173], v[182:185], v[126:129]
	v_mfma_f32_16x16x32_bf16 v[130:133], v[158:161], v[198:201], v[130:133]
	v_mfma_f32_16x16x32_bf16 v[134:137], v[162:165], v[198:201], v[134:137]
	v_mfma_f32_16x16x32_bf16 v[150:153], v[166:169], v[198:201], v[150:153]
	v_mfma_f32_16x16x32_bf16 v[154:157], v[170:173], v[198:201], v[154:157]
	s_waitcnt vmcnt(0)
	v_mfma_f32_16x16x32_bf16 v[82:85], v[202:205], v[218:221], v[82:85]
	v_mfma_f32_16x16x32_bf16 v[86:89], v[206:209], v[218:221], v[86:89]
	v_mfma_f32_16x16x32_bf16 v[90:93], v[210:213], v[218:221], v[90:93]
	v_mfma_f32_16x16x32_bf16 v[94:97], v[214:217], v[218:221], v[94:97]
	v_mfma_f32_16x16x32_bf16 v[98:101], v[202:205], v[222:225], v[98:101]
	v_mfma_f32_16x16x32_bf16 v[102:105], v[206:209], v[222:225], v[102:105]
	v_mfma_f32_16x16x32_bf16 v[106:109], v[210:213], v[222:225], v[106:109]
	v_mfma_f32_16x16x32_bf16 v[110:113], v[214:217], v[222:225], v[110:113]
	v_mfma_f32_16x16x32_bf16 v[114:117], v[202:205], v[226:229], v[114:117]
	v_mfma_f32_16x16x32_bf16 v[118:121], v[206:209], v[226:229], v[118:121]
	v_mfma_f32_16x16x32_bf16 v[122:125], v[210:213], v[226:229], v[122:125]
	v_mfma_f32_16x16x32_bf16 v[126:129], v[214:217], v[226:229], v[126:129]
	v_mfma_f32_16x16x32_bf16 v[130:133], v[202:205], v[230:233], v[130:133]
	v_mfma_f32_16x16x32_bf16 v[134:137], v[206:209], v[230:233], v[134:137]
	v_mfma_f32_16x16x32_bf16 v[150:153], v[210:213], v[230:233], v[150:153]
	v_mfma_f32_16x16x32_bf16 v[154:157], v[214:217], v[230:233], v[154:157]
	s_cmp_gt_i32 s7, 23
	s_cbranch_scc1 .Lcg7_nopf
; template <int MODE>
; DEV void cgemm_tile(const Fr& F, const bf16_t* A, const bf16_t* Bt, int K, int rb, int cb, bf16_t* O, int ldc) {
;     ...
;         if (MODE == 0) brow[ni] = cb * 64 + ni * 16;
;         else { const int j = cb * 32 + (ni & 1) * 16; brow[ni] = (j >> 7) * 256 + (ni >> 1) * 128 + (j & 127); }
;     }
;     const int kslice = K >> 3, steps = kslice >> 5;
;     const bf16_t* ap = A + (size_t)(arow0 + fr) * K + w * kslice + 8 * fq;
;     const bf16_t* bp = Bt + (size_t)fr * K + w * kslice + 8 * fq;
;     f32x4 acc[4][4];
; #pragma unroll
;     for (int mi = 0; mi < 4; ++mi)
; #pragma unroll
;         for (int ni = 0; ni < 4; ++ni) acc[mi][ni] = (f32x4){0.f, 0.f, 0.f, 0.f};
;     int s = 0;
;     for (; s + 4 <= steps; s += 4) cg_chunk<4>(acc, ap + s * 32, bp + s * 32, brow, K);
	s_add_i32 s100, s6, 0x800
	s_add_i32 s101, s0, 0x400
	s_and_b32 s1, s100, 0xffffff00
	s_and_b32 s16, s101, 0x60
	s_or_b32 s16, s16, s1
	s_ashr_i32 s17, s16, 31
	s_lshl_b64 s[18:19], s[16:17], 11
	v_lshl_add_u64 v[48:49], v[20:21], 0, s[18:19]
	s_or_b32 s18, s16, 16
	s_or_b32 s20, s16, 0x80
	s_ashr_i32 s19, s18, 31
	s_or_b32 s16, s16, 0x90
	s_ashr_i32 s21, s20, 31
	s_lshl_b64 s[18:19], s[18:19], 11
	s_ashr_i32 s17, s16, 31
	v_lshl_add_u64 v[54:55], v[20:21], 0, s[18:19]
	s_lshl_b64 s[18:19], s[20:21], 11
	s_lshl_b64 s[16:17], s[16:17], 11
	v_lshl_add_u64 v[52:53], v[20:21], 0, s[18:19]
	v_lshl_add_u64 v[50:51], v[20:21], 0, s[16:17]
	global_load_dwordx4 v[158:161], v[48:49], off
	global_load_dwordx4 v[162:165], v[54:55], off
	global_load_dwordx4 v[166:169], v[52:53], off
	global_load_dwordx4 v[170:173], v[50:51], off
	global_load_dwordx4 v[174:177], v[18:19], off
	global_load_dwordx4 v[178:181], v[22:23], off
	global_load_dwordx4 v[182:185], v[24:25], off
	global_load_dwordx4 v[198:201], v[26:27], off
	global_load_dwordx4 v[202:205], v[48:49], off offset:64
	global_load_dwordx4 v[206:209], v[54:55], off offset:64
	global_load_dwordx4 v[210:213], v[52:53], off offset:64
	global_load_dwordx4 v[214:217], v[50:51], off offset:64
	global_load_dwordx4 v[218:221], v[18:19], off offset:64
	global_load_dwordx4 v[222:225], v[22:23], off offset:64
	global_load_dwordx4 v[226:229], v[24:25], off offset:64
	global_load_dwordx4 v[230:233], v[26:27], off offset:64
; #define LAS __attribute__((address_space(3)))
; DEV unsigned pk2(float lo, float hi) { unsigned r; asm("v_cvt_pk_bf16_f32 %0, %1, %2" : "=v"(r) : "v"(lo), "v"(hi)); return r; }
; DEV float fsilu(float x) { return x * fsigmoid(x); }
; template <int MODE>
; DEV void cgemm_tile(const Fr& F, const bf16_t* A, const bf16_t* Bt, int K, int rb, int cb, bf16_t* O, int ldc) {
;     ...
; #pragma unroll
;     for (int mi = 0; mi < 4; ++mi)
; #pragma unroll
;         for (int ni = 0; ni < 4; ++ni) *(LAS f32x4*)(part + (w * 64 + 16 * mi + fr) * 64 + ((16 * ni + 4 * fq) ^ (fr << 2))) = acc[mi][ni];
;     __syncthreads();
;     { const int row = F.tid >> 3, c8 = (F.tid & 7) * 8, sw = (row & 15) << 2;
;       if (MODE == 0) {
;           f32x4 s0 = (f32x4){0.f, 0.f, 0.f, 0.f}, s1 = s0;
; #pragma unroll
;           for (int ww = 0; ww < 8; ++ww) { s0 += *(const LAS f32x4*)(part + (ww * 64 + row) * 64 + (c8 ^ sw)); s1 += *(const LAS f32x4*)(part + (ww * 64 + row) * 64 + ((c8 + 4) ^ sw)); }
;           u32x4 o; o.x = pk2(s0[0], s0[1]); o.y = pk2(s0[2], s0[3]); o.z = pk2(s1[0], s1[1]); o.w = pk2(s1[2], s1[3]);
;           *(u32x4*)(O + (size_t)(arow0 + row) * ldc + cb * 64 + c8) = o;
;       } else if (c8 < 32) {
;           f32x4 g0 = (f32x4){0.f, 0.f, 0.f, 0.f}, g1 = g0, u0 = g0, u1 = g0;
; #pragma unroll
;           for (int ww = 0; ww < 8; ++ww) { const LAS float* pr = part + (ww * 64 + row) * 64;
;               g0 += *(const LAS f32x4*)(pr + (c8 ^ sw)); g1 += *(const LAS f32x4*)(pr + ((c8 + 4) ^ sw)); u0 += *(const LAS f32x4*)(pr + ((c8 + 32) ^ sw)); u1 += *(const LAS f32x4*)(pr + ((c8 + 36) ^ sw)); }
;           float o[8];
; #pragma unroll
;           for (int j = 0; j < 4; ++j) { o[j] = fsilu(g0[j]) * u0[j]; o[4 + j] = fsilu(g1[j]) * u1[j]; }
;           u32x4 ov; ov.x = pk2(o[0], o[1]); ov.y = pk2(o[2], o[3]); ov.z = pk2(o[4], o[5]); ov.w = pk2(o[6], o[7]);
;           *(u32x4*)(O + (size_t)(arow0 + row) * ldc + cb * 32 + c8) = ov;
;       } }
.Lcg7_nopf:
	ds_write_b128 v57, v[82:85]
	ds_write_b128 v58, v[86:89]
	ds_write_b128 v59, v[90:93]
	ds_write_b128 v60, v[94:97]
	ds_write_b128 v57, v[98:101] offset:4096
	ds_write_b128 v58, v[102:105] offset:4096
	ds_write_b128 v59, v[106:109] offset:4096
	ds_write_b128 v60, v[110:113] offset:4096
	ds_write_b128 v57, v[114:117] offset:8192
	ds_write_b128 v58, v[118:121] offset:8192
	ds_write_b128 v59, v[122:125] offset:8192
	ds_write_b128 v60, v[126:129] offset:8192
	ds_write_b128 v57, v[130:133] offset:12288
	ds_write_b128 v58, v[134:137] offset:12288
	ds_write_b128 v59, v[150:153] offset:12288
	ds_write_b128 v60, v[154:157] offset:12288
	s_waitcnt lgkmcnt(0)
	s_barrier
	s_and_saveexec_b64 s[16:17], vcc
	s_cbranch_execz .LBB0_1261
	s_ashr_i32 s1, s0, 31
	ds_read_b128 v[82:85], v61
	ds_read_b128 v[86:89], v62
	ds_read_b128 v[90:93], v63
	ds_read_b128 v[94:97], v64
	ds_read_b128 v[98:101], v61 offset:16384
	ds_read_b128 v[102:105], v62 offset:16384
	ds_read_b128 v[106:109], v63 offset:16384
	ds_read_b128 v[110:113], v64 offset:16384
	ds_read_b128 v[114:117], v61 offset:32768
	ds_read_b128 v[118:121], v62 offset:32768
	ds_read_b128 v[122:125], v63 offset:32768
	ds_read_b128 v[126:129], v64 offset:32768
	ds_read_b128 v[130:133], v61 offset:49152
	ds_read_b128 v[134:137], v62 offset:49152
	ds_read_b128 v[150:153], v63 offset:49152
	ds_read_b128 v[154:157], v64 offset:49152
	s_waitcnt lgkmcnt(15)
	v_pk_add_f32 v[6:7], v[84:85], 0 op_sel_hi:[1,0]
	v_pk_add_f32 v[8:9], v[82:83], 0 op_sel_hi:[1,0]
	s_waitcnt lgkmcnt(14)
	v_pk_add_f32 v[10:11], v[88:89], 0 op_sel_hi:[1,0]
	v_pk_add_f32 v[12:13], v[86:87], 0 op_sel_hi:[1,0]
	s_waitcnt lgkmcnt(13)
	v_pk_add_f32 v[14:15], v[92:93], 0 op_sel_hi:[1,0]
	v_pk_add_f32 v[16:17], v[90:91], 0 op_sel_hi:[1,0]
	s_waitcnt lgkmcnt(12)
	v_pk_add_f32 v[48:49], v[96:97], 0 op_sel_hi:[1,0]
	v_pk_add_f32 v[50:51], v[94:95], 0 op_sel_hi:[1,0]
	s_waitcnt lgkmcnt(11)
	v_pk_add_f32 v[6:7], v[6:7], v[100:101]
	v_pk_add_f32 v[8:9], v[8:9], v[98:99]
	s_waitcnt lgkmcnt(10)
	v_pk_add_f32 v[10:11], v[10:11], v[104:105]
	v_pk_add_f32 v[12:13], v[12:13], v[102:103]
	s_waitcnt lgkmcnt(9)
	v_pk_add_f32 v[14:15], v[14:15], v[108:109]
	v_pk_add_f32 v[16:17], v[16:17], v[106:107]
	s_waitcnt lgkmcnt(8)
	v_pk_add_f32 v[48:49], v[48:49], v[112:113]
	v_pk_add_f32 v[50:51], v[50:51], v[110:111]
	s_waitcnt lgkmcnt(7)
	v_pk_add_f32 v[6:7], v[6:7], v[116:117]
	v_pk_add_f32 v[8:9], v[8:9], v[114:115]
	s_waitcnt lgkmcnt(6)
	v_pk_add_f32 v[10:11], v[10:11], v[120:121]
	v_pk_add_f32 v[12:13], v[12:13], v[118:119]
	s_waitcnt lgkmcnt(5)
	v_pk_add_f32 v[14:15], v[14:15], v[124:125]
	v_pk_add_f32 v[16:17], v[16:17], v[122:123]
	s_waitcnt lgkmcnt(4)
	v_pk_add_f32 v[48:49], v[48:49], v[128:129]
	v_pk_add_f32 v[50:51], v[50:51], v[126:127]
	s_waitcnt lgkmcnt(3)
	v_pk_add_f32 v[6:7], v[6:7], v[132:133]
	v_pk_add_f32 v[8:9], v[8:9], v[130:131]
	s_waitcnt lgkmcnt(2)
	v_pk_add_f32 v[10:11], v[10:11], v[136:137]
	v_pk_add_f32 v[12:13], v[12:13], v[134:135]
	s_waitcnt lgkmcnt(1)
	v_pk_add_f32 v[14:15], v[14:15], v[152:153]
	v_pk_add_f32 v[16:17], v[16:17], v[150:151]
	s_waitcnt lgkmcnt(0)
	v_pk_add_f32 v[48:49], v[48:49], v[156:157]
	v_pk_add_f32 v[50:51], v[50:51], v[154:155]
	ds_read_b128 v[82:85], v65
	ds_read_b128 v[86:89], v66
	ds_read_b128 v[90:93], v67
	ds_read_b128 v[94:97], v68
	ds_read_b128 v[98:101], v69
	ds_read_b128 v[102:105], v70
	ds_read_b128 v[106:109], v71
	ds_read_b128 v[110:113], v72
	ds_read_b128 v[114:117], v73
	ds_read_b128 v[118:121], v74
	ds_read_b128 v[122:125], v75
	ds_read_b128 v[126:129], v76
	s_waitcnt lgkmcnt(11)
	v_pk_add_f32 v[6:7], v[6:7], v[84:85]
	v_pk_add_f32 v[8:9], v[8:9], v[82:83]
	s_waitcnt lgkmcnt(10)
	v_pk_add_f32 v[10:11], v[10:11], v[88:89]
	v_pk_add_f32 v[12:13], v[12:13], v[86:87]
	s_waitcnt lgkmcnt(9)
	v_pk_add_f32 v[14:15], v[14:15], v[92:93]
	v_pk_add_f32 v[16:17], v[16:17], v[90:91]
	s_waitcnt lgkmcnt(8)
	v_pk_add_f32 v[48:49], v[48:49], v[96:97]
	v_pk_add_f32 v[50:51], v[50:51], v[94:95]
	s_waitcnt lgkmcnt(7)
	v_pk_add_f32 v[6:7], v[6:7], v[100:101]
	v_pk_add_f32 v[8:9], v[8:9], v[98:99]
	s_waitcnt lgkmcnt(6)
	v_pk_add_f32 v[10:11], v[10:11], v[104:105]
	v_pk_add_f32 v[12:13], v[12:13], v[102:103]
	s_waitcnt lgkmcnt(5)
	v_pk_add_f32 v[14:15], v[14:15], v[108:109]
	v_pk_add_f32 v[16:17], v[16:17], v[106:107]
	s_waitcnt lgkmcnt(4)
	v_pk_add_f32 v[48:49], v[48:49], v[112:113]
	v_pk_add_f32 v[50:51], v[50:51], v[110:111]
	s_waitcnt lgkmcnt(3)
	v_pk_add_f32 v[6:7], v[6:7], v[116:117]
	v_pk_add_f32 v[8:9], v[8:9], v[114:115]
	s_waitcnt lgkmcnt(2)
	v_pk_add_f32 v[10:11], v[10:11], v[120:121]
	v_pk_add_f32 v[12:13], v[12:13], v[118:119]
	s_waitcnt lgkmcnt(1)
	v_pk_add_f32 v[14:15], v[14:15], v[124:125]
	v_pk_add_f32 v[16:17], v[16:17], v[122:123]
	s_waitcnt lgkmcnt(0)
	v_pk_add_f32 v[48:49], v[48:49], v[128:129]
	v_pk_add_f32 v[50:51], v[50:51], v[126:127]
	ds_read_b128 v[2:5], v77
	s_waitcnt lgkmcnt(0)
	v_pk_add_f32 v[52:53], v[6:7], v[4:5]
	ds_read_b128 v[4:7], v78
	v_pk_add_f32 v[8:9], v[8:9], v[2:3]
	s_waitcnt lgkmcnt(0)
	v_pk_add_f32 v[2:3], v[10:11], v[6:7]
	v_pk_add_f32 v[10:11], v[12:13], v[4:5]
	ds_read_b128 v[4:7], v79
	s_waitcnt lgkmcnt(0)
	v_pk_add_f32 v[12:13], v[14:15], v[6:7]
	v_pk_add_f32 v[14:15], v[16:17], v[4:5]
	v_mul_f32_e32 v16, 0xbfb8aa3b, v8
	v_exp_f32_e32 v16, v16
	ds_read_b128 v[4:7], v80
	v_add_f32_e32 v16, 1.0, v16
	v_rcp_f32_e32 v16, v16
	s_waitcnt lgkmcnt(0)
	v_pk_add_f32 v[4:5], v[50:51], v[4:5]
	v_pk_add_f32 v[6:7], v[48:49], v[6:7]
	v_mul_f32_e32 v8, v8, v16
	v_mul_f32_e32 v8, v14, v8
	v_mul_f32_e32 v14, 0xbfb8aa3b, v10
	v_exp_f32_e32 v14, v14
	s_nop 0
	v_add_f32_e32 v14, 1.0, v14
	v_rcp_f32_e32 v14, v14
	s_nop 0
	v_mul_f32_e32 v10, v10, v14
	v_mul_f32_e32 v4, v4, v10
	v_mul_f32_e32 v10, 0xbfb8aa3b, v9
	v_exp_f32_e32 v10, v10
	s_nop 0
	v_add_f32_e32 v10, 1.0, v10
	v_rcp_f32_e32 v10, v10
	s_nop 0
	v_mul_f32_e32 v9, v9, v10
	v_mul_f32_e32 v10, 0xbfb8aa3b, v11
	v_exp_f32_e32 v10, v10
	v_mul_f32_e32 v9, v15, v9
	v_add_f32_e32 v10, 1.0, v10
	v_rcp_f32_e32 v10, v10
	s_nop 0
	v_mul_f32_e32 v10, v11, v10
	v_mul_f32_e32 v11, 0xbfb8aa3b, v2
	v_exp_f32_e32 v11, v11
	v_mul_f32_e32 v5, v5, v10
	v_mul_f32_e32 v10, 0xbfb8aa3b, v52
	v_exp_f32_e32 v10, v10
	v_add_f32_e32 v11, 1.0, v11
	v_rcp_f32_e32 v11, v11
	v_cvt_pk_bf16_f32 v4, v4, v5
	v_add_f32_e32 v10, 1.0, v10
	v_rcp_f32_e32 v10, v10
	v_mul_f32_e32 v2, v2, v11
	v_mul_f32_e32 v6, v6, v2
	v_mul_f32_e32 v2, 0xbfb8aa3b, v53
	v_exp_f32_e32 v2, v2
	v_mul_f32_e32 v10, v52, v10
	v_mul_f32_e32 v10, v12, v10
	v_add_f32_e32 v2, 1.0, v2
	v_rcp_f32_e32 v2, v2
	s_nop 0
	v_mul_f32_e32 v2, v53, v2
	v_mul_f32_e32 v11, v13, v2
	v_mul_f32_e32 v2, 0xbfb8aa3b, v3
	v_exp_f32_e32 v2, v2
	s_nop 0
	v_add_f32_e32 v2, 1.0, v2
	v_rcp_f32_e32 v2, v2
	s_nop 0
	v_mul_f32_e32 v2, v3, v2
	v_mul_f32_e32 v7, v7, v2
	v_cvt_pk_bf16_f32 v5, v6, v7
	v_lshl_add_u64 v[6:7], s[0:1], 1, v[46:47]
	v_cvt_pk_bf16_f32 v2, v8, v9
	v_cvt_pk_bf16_f32 v3, v10, v11
	global_store_dwordx4 v[6:7], v[2:5], off
	s_branch .LBB0_1261
